# SwiGLU GEMM K-loop: last LDS-DMA piece of each 6-piece load phase issued from the middle of the following MFMA phase (vmcnt 8 to 7 there)
# baseline (speedup 1.0000x reference)
.LBB0_361:
	s_add_u32 s16, s14, 0xfffc0080
	s_addc_u32 s17, s15, -1
	s_add_i32 s45, 0, 0x10000
	s_cmp_eq_u32 s44, 12
	s_cselect_b32 s21, s38, s17
	s_cselect_b32 s20, s39, s16
	v_add_u32_e32 v148, s45, v151
	s_cselect_b32 s17, s40, s43
	s_cselect_b32 s16, s41, s42
	s_add_i32 s48, 0, 0x14000
	ds_read_b128 v[144:147], v148
	ds_read_b128 v[160:163], v148 offset:1024
	ds_read_b128 v[164:167], v148 offset:2048
	ds_read_b128 v[168:171], v148 offset:3072
	v_add_u32_e32 v148, s48, v151
	ds_read_b128 v[172:175], v148
	ds_read_b128 v[176:179], v148 offset:1024
	ds_read_b128 v[180:183], v148 offset:2048
	ds_read_b128 v[184:187], v148 offset:3072
	v_lshl_add_u64 v[148:149], s[14:15], 0, v[142:143]
	s_add_i32 m0, s26, 0xc000
	ds_read_b128 v[188:191], v159
	ds_read_b128 v[192:195], v159 offset:1024
	ds_read_b128 v[196:199], v159 offset:2048
	ds_read_b128 v[200:203], v159 offset:3072
	ds_read_b128 v[204:207], v159 offset:4096
	ds_read_b128 v[208:211], v159 offset:5120
	ds_read_b128 v[212:215], v159 offset:6144
	ds_read_b128 v[216:219], v159 offset:7168
	global_load_lds_dwordx4 v[148:149], off
	v_lshl_add_u64 v[148:149], s[14:15], 0, v[140:141]
	s_add_i32 m0, s26, 0xe000
	s_nop 0
	global_load_lds_dwordx4 v[148:149], off
	s_waitcnt vmcnt(8)
	s_waitcnt lgkmcnt(0)
	s_barrier
	s_setprio 1
	s_waitcnt lgkmcnt(0)
	v_mfma_f32_16x16x32_bf16 v[126:129], v[144:147], v[188:191], v[126:129]
	v_mfma_f32_16x16x32_bf16 v[122:125], v[164:167], v[188:191], v[122:125]
	v_mfma_f32_16x16x32_bf16 v[110:113], v[144:147], v[196:199], v[110:113]
	v_mfma_f32_16x16x32_bf16 v[106:109], v[164:167], v[196:199], v[106:109]
	v_mfma_f32_16x16x32_bf16 v[94:97], v[144:147], v[204:207], v[94:97]
	v_mfma_f32_16x16x32_bf16 v[90:93], v[164:167], v[204:207], v[90:93]
	v_mfma_f32_16x16x32_bf16 v[78:81], v[144:147], v[212:215], v[78:81]
	v_mfma_f32_16x16x32_bf16 v[74:77], v[164:167], v[212:215], v[74:77]
	v_mfma_f32_16x16x32_bf16 v[126:129], v[160:163], v[192:195], v[126:129]
	v_mfma_f32_16x16x32_bf16 v[122:125], v[168:171], v[192:195], v[122:125]
	v_mfma_f32_16x16x32_bf16 v[110:113], v[160:163], v[200:203], v[110:113]
	v_mfma_f32_16x16x32_bf16 v[106:109], v[168:171], v[200:203], v[106:109]
	v_mfma_f32_16x16x32_bf16 v[94:97], v[160:163], v[208:211], v[94:97]
	v_mfma_f32_16x16x32_bf16 v[90:93], v[168:171], v[208:211], v[90:93]
	v_mfma_f32_16x16x32_bf16 v[78:81], v[160:163], v[216:219], v[78:81]
	v_mfma_f32_16x16x32_bf16 v[74:77], v[168:171], v[216:219], v[74:77]
	s_setprio 0
	s_setprio 1
	v_mfma_f32_16x16x32_bf16 v[118:121], v[172:175], v[188:191], v[118:121]
	v_mfma_f32_16x16x32_bf16 v[114:117], v[180:183], v[188:191], v[114:117]
	v_mfma_f32_16x16x32_bf16 v[102:105], v[172:175], v[196:199], v[102:105]
	v_mfma_f32_16x16x32_bf16 v[98:101], v[180:183], v[196:199], v[98:101]
	v_mfma_f32_16x16x32_bf16 v[86:89], v[172:175], v[204:207], v[86:89]
	v_mfma_f32_16x16x32_bf16 v[82:85], v[180:183], v[204:207], v[82:85]
	v_mfma_f32_16x16x32_bf16 v[70:73], v[172:175], v[212:215], v[70:73]
	v_mfma_f32_16x16x32_bf16 v[66:69], v[180:183], v[212:215], v[66:69]
	v_mfma_f32_16x16x32_bf16 v[118:121], v[176:179], v[192:195], v[118:121]
	v_mfma_f32_16x16x32_bf16 v[114:117], v[184:187], v[192:195], v[114:117]
	v_mfma_f32_16x16x32_bf16 v[102:105], v[176:179], v[200:203], v[102:105]
	v_mfma_f32_16x16x32_bf16 v[98:101], v[184:187], v[200:203], v[98:101]
	v_mfma_f32_16x16x32_bf16 v[86:89], v[176:179], v[208:211], v[86:89]
	v_mfma_f32_16x16x32_bf16 v[82:85], v[184:187], v[208:211], v[82:85]
	v_mfma_f32_16x16x32_bf16 v[70:73], v[176:179], v[216:219], v[70:73]
	v_mfma_f32_16x16x32_bf16 v[66:69], v[184:187], v[216:219], v[66:69]
	s_setprio 0
	s_barrier
	s_add_i32 s45, s45, s24
	v_lshl_add_u64 v[148:149], s[16:17], 0, v[134:135]
	s_mov_b32 m0, s45
	ds_read_b128 v[188:191], v159 offset:16384
	ds_read_b128 v[192:195], v159 offset:17408
	ds_read_b128 v[196:199], v159 offset:18432
	ds_read_b128 v[200:203], v159 offset:19456
	ds_read_b128 v[204:207], v159 offset:20480
	ds_read_b128 v[208:211], v159 offset:21504
	ds_read_b128 v[212:215], v159 offset:22528
	ds_read_b128 v[216:219], v159 offset:23552
	global_load_lds_dwordx4 v[148:149], off
	s_add_i32 m0, s45, 0x2000
	s_add_u32 s46, s16, 0x40000
	v_lshl_add_u64 v[152:153], s[16:17], 0, v[130:131]
	s_addc_u32 s47, s17, 0
	s_add_i32 s45, s48, s24
	global_load_lds_dwordx4 v[152:153], off
	v_lshl_add_u64 v[156:157], s[46:47], 0, v[134:135]
	s_mov_b32 m0, s45
	v_lshl_add_u64 v[220:221], s[20:21], 0, v[132:133]
	global_load_lds_dwordx4 v[156:157], off
	v_lshl_add_u64 v[156:157], s[46:47], 0, v[130:131]
	s_add_i32 m0, s45, 0x2000
	s_nop 0
	global_load_lds_dwordx4 v[156:157], off
	v_lshl_add_u64 v[156:157], s[20:21], 0, v[136:137]
	s_mov_b32 m0, s26
	s_nop 0
	global_load_lds_dwordx4 v[156:157], off
	s_waitcnt vmcnt(7)
	s_waitcnt lgkmcnt(0)
	s_barrier
	s_setprio 1
	s_waitcnt lgkmcnt(0)
	v_mfma_f32_16x16x32_bf16 v[62:65], v[144:147], v[188:191], v[62:65]
	v_mfma_f32_16x16x32_bf16 v[58:61], v[164:167], v[188:191], v[58:61]
	v_mfma_f32_16x16x32_bf16 v[46:49], v[144:147], v[196:199], v[46:49]
	v_mfma_f32_16x16x32_bf16 v[42:45], v[164:167], v[196:199], v[42:45]
	v_mfma_f32_16x16x32_bf16 v[30:33], v[144:147], v[204:207], v[30:33]
	v_mfma_f32_16x16x32_bf16 v[26:29], v[164:167], v[204:207], v[26:29]
	v_mfma_f32_16x16x32_bf16 v[14:17], v[144:147], v[212:215], v[14:17]
	v_mfma_f32_16x16x32_bf16 v[10:13], v[164:167], v[212:215], v[10:13]
	v_mfma_f32_16x16x32_bf16 v[62:65], v[160:163], v[192:195], v[62:65]
	v_mfma_f32_16x16x32_bf16 v[58:61], v[168:171], v[192:195], v[58:61]
	v_mfma_f32_16x16x32_bf16 v[46:49], v[160:163], v[200:203], v[46:49]
	v_mfma_f32_16x16x32_bf16 v[42:45], v[168:171], v[200:203], v[42:45]
	v_mfma_f32_16x16x32_bf16 v[30:33], v[160:163], v[208:211], v[30:33]
	v_mfma_f32_16x16x32_bf16 v[26:29], v[168:171], v[208:211], v[26:29]
	v_mfma_f32_16x16x32_bf16 v[14:17], v[160:163], v[216:219], v[14:17]
	v_mfma_f32_16x16x32_bf16 v[10:13], v[168:171], v[216:219], v[10:13]
	s_mov_b32 m0, s27
	s_nop 0
	global_load_lds_dwordx4 v[220:221], off
	s_setprio 0
	s_setprio 1
	v_mfma_f32_16x16x32_bf16 v[54:57], v[172:175], v[188:191], v[54:57]
	v_mfma_f32_16x16x32_bf16 v[50:53], v[180:183], v[188:191], v[50:53]
	v_mfma_f32_16x16x32_bf16 v[38:41], v[172:175], v[196:199], v[38:41]
	v_mfma_f32_16x16x32_bf16 v[34:37], v[180:183], v[196:199], v[34:37]
	v_mfma_f32_16x16x32_bf16 v[22:25], v[172:175], v[204:207], v[22:25]
	v_mfma_f32_16x16x32_bf16 v[18:21], v[180:183], v[204:207], v[18:21]
	v_mfma_f32_16x16x32_bf16 v[6:9], v[172:175], v[212:215], v[6:9]
	v_mfma_f32_16x16x32_bf16 v[2:5], v[180:183], v[212:215], v[2:5]
	v_mfma_f32_16x16x32_bf16 v[54:57], v[176:179], v[192:195], v[54:57]
	v_mfma_f32_16x16x32_bf16 v[50:53], v[184:187], v[192:195], v[50:53]
	v_mfma_f32_16x16x32_bf16 v[38:41], v[176:179], v[200:203], v[38:41]
	v_mfma_f32_16x16x32_bf16 v[34:37], v[184:187], v[200:203], v[34:37]
	v_mfma_f32_16x16x32_bf16 v[22:25], v[176:179], v[208:211], v[22:25]
	v_mfma_f32_16x16x32_bf16 v[18:21], v[184:187], v[208:211], v[18:21]
	v_mfma_f32_16x16x32_bf16 v[6:9], v[176:179], v[216:219], v[6:9]
	v_mfma_f32_16x16x32_bf16 v[2:5], v[184:187], v[216:219], v[2:5]
	s_setprio 0
	s_barrier
	s_add_i32 s45, 0, 0x18000
	v_add_u32_e32 v150, s45, v151
	s_add_i32 s46, 0, 0x1c000
	ds_read_b128 v[144:147], v150
	ds_read_b128 v[160:163], v150 offset:1024
	ds_read_b128 v[164:167], v150 offset:2048
	ds_read_b128 v[168:171], v150 offset:3072
	v_add_u32_e32 v150, s46, v151
	ds_read_b128 v[172:175], v150
	ds_read_b128 v[176:179], v150 offset:1024
	ds_read_b128 v[180:183], v150 offset:2048
	ds_read_b128 v[184:187], v150 offset:3072
	s_add_u32 s20, s20, 0x40000
	s_addc_u32 s21, s21, 0
	s_mov_b32 m0, s28
	v_lshl_add_u64 v[222:223], s[20:21], 0, v[136:137]
	ds_read_b128 v[188:191], v159 offset:32768
	ds_read_b128 v[192:195], v159 offset:33792
	ds_read_b128 v[196:199], v159 offset:34816
	ds_read_b128 v[200:203], v159 offset:35840
	ds_read_b128 v[204:207], v159 offset:36864
	ds_read_b128 v[208:211], v159 offset:37888
	ds_read_b128 v[212:215], v159 offset:38912
	ds_read_b128 v[216:219], v159 offset:39936
	global_load_lds_dwordx4 v[222:223], off
	v_lshl_add_u64 v[222:223], s[20:21], 0, v[132:133]
	s_mov_b32 m0, s29
	s_nop 0
	global_load_lds_dwordx4 v[222:223], off
	s_waitcnt vmcnt(8)
	s_waitcnt lgkmcnt(0)
	s_barrier
	s_setprio 1
	s_waitcnt lgkmcnt(0)
	v_mfma_f32_16x16x32_bf16 v[126:129], v[144:147], v[188:191], v[126:129]
	v_mfma_f32_16x16x32_bf16 v[122:125], v[164:167], v[188:191], v[122:125]
	v_mfma_f32_16x16x32_bf16 v[110:113], v[144:147], v[196:199], v[110:113]
	v_mfma_f32_16x16x32_bf16 v[106:109], v[164:167], v[196:199], v[106:109]
	v_mfma_f32_16x16x32_bf16 v[94:97], v[144:147], v[204:207], v[94:97]
	v_mfma_f32_16x16x32_bf16 v[90:93], v[164:167], v[204:207], v[90:93]
	v_mfma_f32_16x16x32_bf16 v[78:81], v[144:147], v[212:215], v[78:81]
	v_mfma_f32_16x16x32_bf16 v[74:77], v[164:167], v[212:215], v[74:77]
	v_mfma_f32_16x16x32_bf16 v[126:129], v[160:163], v[192:195], v[126:129]
	v_mfma_f32_16x16x32_bf16 v[122:125], v[168:171], v[192:195], v[122:125]
	v_mfma_f32_16x16x32_bf16 v[110:113], v[160:163], v[200:203], v[110:113]
	v_mfma_f32_16x16x32_bf16 v[106:109], v[168:171], v[200:203], v[106:109]
	v_mfma_f32_16x16x32_bf16 v[94:97], v[160:163], v[208:211], v[94:97]
	v_mfma_f32_16x16x32_bf16 v[90:93], v[168:171], v[208:211], v[90:93]
	v_mfma_f32_16x16x32_bf16 v[78:81], v[160:163], v[216:219], v[78:81]
	v_mfma_f32_16x16x32_bf16 v[74:77], v[168:171], v[216:219], v[74:77]
	s_setprio 0
	s_setprio 1
	v_mfma_f32_16x16x32_bf16 v[118:121], v[172:175], v[188:191], v[118:121]
	v_mfma_f32_16x16x32_bf16 v[114:117], v[180:183], v[188:191], v[114:117]
	v_mfma_f32_16x16x32_bf16 v[102:105], v[172:175], v[196:199], v[102:105]
	v_mfma_f32_16x16x32_bf16 v[98:101], v[180:183], v[196:199], v[98:101]
	v_mfma_f32_16x16x32_bf16 v[86:89], v[172:175], v[204:207], v[86:89]
	v_mfma_f32_16x16x32_bf16 v[82:85], v[180:183], v[204:207], v[82:85]
	v_mfma_f32_16x16x32_bf16 v[70:73], v[172:175], v[212:215], v[70:73]
	v_mfma_f32_16x16x32_bf16 v[66:69], v[180:183], v[212:215], v[66:69]
	v_mfma_f32_16x16x32_bf16 v[118:121], v[176:179], v[192:195], v[118:121]
	v_mfma_f32_16x16x32_bf16 v[114:117], v[184:187], v[192:195], v[114:117]
	v_mfma_f32_16x16x32_bf16 v[102:105], v[176:179], v[200:203], v[102:105]
	v_mfma_f32_16x16x32_bf16 v[98:101], v[184:187], v[200:203], v[98:101]
	v_mfma_f32_16x16x32_bf16 v[86:89], v[176:179], v[208:211], v[86:89]
	v_mfma_f32_16x16x32_bf16 v[82:85], v[184:187], v[208:211], v[82:85]
	v_mfma_f32_16x16x32_bf16 v[70:73], v[176:179], v[216:219], v[70:73]
	v_mfma_f32_16x16x32_bf16 v[66:69], v[184:187], v[216:219], v[66:69]
	s_setprio 0
	s_barrier
	s_add_i32 s20, s45, s24
	v_lshl_add_u64 v[148:149], v[148:149], 0, s[90:91]
	s_mov_b32 m0, s20
	ds_read_b128 v[188:191], v159 offset:49152
	ds_read_b128 v[192:195], v159 offset:50176
	ds_read_b128 v[196:199], v159 offset:51200
	ds_read_b128 v[200:203], v159 offset:52224
	ds_read_b128 v[204:207], v159 offset:53248
	ds_read_b128 v[208:211], v159 offset:54272
	ds_read_b128 v[212:215], v159 offset:55296
	ds_read_b128 v[216:219], v159 offset:56320
	global_load_lds_dwordx4 v[148:149], off
	s_add_i32 m0, s20, 0x2000
	s_add_u32 s16, s16, 0x40080
	v_lshl_add_u64 v[148:149], v[152:153], 0, s[90:91]
	s_addc_u32 s17, s17, 0
	s_add_i32 s20, s46, s24
	global_load_lds_dwordx4 v[148:149], off
	v_lshl_add_u64 v[148:149], s[16:17], 0, v[134:135]
	s_mov_b32 m0, s20
	s_nop 0
	global_load_lds_dwordx4 v[148:149], off
	v_lshl_add_u64 v[148:149], s[16:17], 0, v[130:131]
	s_add_i32 m0, s20, 0x2000
	s_nop 0
	global_load_lds_dwordx4 v[148:149], off
	v_lshl_add_u64 v[148:149], v[156:157], 0, s[90:91]
	s_mov_b32 m0, s31
	s_nop 0
	global_load_lds_dwordx4 v[148:149], off
	v_lshl_add_u64 v[148:149], v[220:221], 0, s[90:91]
	s_waitcnt vmcnt(7)
	s_waitcnt lgkmcnt(0)
	s_barrier
	s_setprio 1
	s_waitcnt lgkmcnt(0)
	v_mfma_f32_16x16x32_bf16 v[62:65], v[144:147], v[188:191], v[62:65]
	v_mfma_f32_16x16x32_bf16 v[58:61], v[164:167], v[188:191], v[58:61]
	v_mfma_f32_16x16x32_bf16 v[46:49], v[144:147], v[196:199], v[46:49]
	v_mfma_f32_16x16x32_bf16 v[42:45], v[164:167], v[196:199], v[42:45]
	v_mfma_f32_16x16x32_bf16 v[30:33], v[144:147], v[204:207], v[30:33]
	v_mfma_f32_16x16x32_bf16 v[26:29], v[164:167], v[204:207], v[26:29]
	v_mfma_f32_16x16x32_bf16 v[14:17], v[144:147], v[212:215], v[14:17]
	v_mfma_f32_16x16x32_bf16 v[10:13], v[164:167], v[212:215], v[10:13]
	v_mfma_f32_16x16x32_bf16 v[62:65], v[160:163], v[192:195], v[62:65]
	v_mfma_f32_16x16x32_bf16 v[58:61], v[168:171], v[192:195], v[58:61]
	v_mfma_f32_16x16x32_bf16 v[46:49], v[160:163], v[200:203], v[46:49]
	v_mfma_f32_16x16x32_bf16 v[42:45], v[168:171], v[200:203], v[42:45]
	v_mfma_f32_16x16x32_bf16 v[30:33], v[160:163], v[208:211], v[30:33]
	v_mfma_f32_16x16x32_bf16 v[26:29], v[168:171], v[208:211], v[26:29]
	v_mfma_f32_16x16x32_bf16 v[14:17], v[160:163], v[216:219], v[14:17]
	v_mfma_f32_16x16x32_bf16 v[10:13], v[168:171], v[216:219], v[10:13]
	s_mov_b32 m0, s33
	s_nop 0
	global_load_lds_dwordx4 v[148:149], off
	s_setprio 0
	s_setprio 1
	v_mfma_f32_16x16x32_bf16 v[54:57], v[172:175], v[188:191], v[54:57]
	v_mfma_f32_16x16x32_bf16 v[50:53], v[180:183], v[188:191], v[50:53]
	v_mfma_f32_16x16x32_bf16 v[38:41], v[172:175], v[196:199], v[38:41]
	v_mfma_f32_16x16x32_bf16 v[34:37], v[180:183], v[196:199], v[34:37]
	v_mfma_f32_16x16x32_bf16 v[22:25], v[172:175], v[204:207], v[22:25]
	v_mfma_f32_16x16x32_bf16 v[18:21], v[180:183], v[204:207], v[18:21]
	v_mfma_f32_16x16x32_bf16 v[6:9], v[172:175], v[212:215], v[6:9]
	v_mfma_f32_16x16x32_bf16 v[2:5], v[180:183], v[212:215], v[2:5]
	v_mfma_f32_16x16x32_bf16 v[54:57], v[176:179], v[192:195], v[54:57]
	v_mfma_f32_16x16x32_bf16 v[50:53], v[184:187], v[192:195], v[50:53]
	v_mfma_f32_16x16x32_bf16 v[38:41], v[176:179], v[200:203], v[38:41]
	v_mfma_f32_16x16x32_bf16 v[34:37], v[184:187], v[200:203], v[34:37]
	v_mfma_f32_16x16x32_bf16 v[22:25], v[176:179], v[208:211], v[22:25]
	v_mfma_f32_16x16x32_bf16 v[18:21], v[184:187], v[208:211], v[18:21]
	v_mfma_f32_16x16x32_bf16 v[6:9], v[176:179], v[216:219], v[6:9]
	v_mfma_f32_16x16x32_bf16 v[2:5], v[184:187], v[216:219], v[2:5]
	s_setprio 0
	s_barrier
	s_add_i32 s44, s44, 2
	s_add_u32 s42, s42, 0x100
	s_addc_u32 s43, s43, 0
	s_add_u32 s14, s14, 0x100
	s_addc_u32 s15, s15, 0
	s_cmp_gt_u32 s44, 13
	s_cbranch_scc0 .LBB0_361
	s_and_b64 vcc, exec, s[6:7]
	s_cbranch_vccz .LBB0_364
	s_barrier
